# scan: kh and b kept as fp16 in the LDS records (one 16-B slot per step), products formed with v_fma_mix_f32: 2 fewer ds_read_b128 per step pair
# speedup vs baseline: 1.0162x; 1.0023x over previous
; #define LAS __attribute__((address_space(3)))
; __device__ __forceinline__ float row16_allsum(float x) { x = ROW_ROR_ADD(x, 8); x = ROW_ROR_ADD(x, 4); x = ROW_ROR_ADD(x, 2); x = ROW_ROR_ADD(x, 1); return x; }
; __device__ __forceinline__ f32x4 h4f(u32x2 r) { const h16x4 hv = __builtin_bit_cast(h16x4, r); return (f32x4){(float)hv[0], (float)hv[1], (float)hv[2], (float)hv[3]}; }
; __device__ __forceinline__ f32x4 b4f(u32x2 r) { return (f32x4){__uint_as_float(r.x << 16), __uint_as_float(r.x & 0xffff0000u), __uint_as_float(r.y << 16), __uint_as_float(r.y & 0xffff0000u)}; }
; __device__ __forceinline__ void scan_cvt_write(const Params& P, int h, const ScanRegs& R, LAS unsigned char* buf, int ll) {
;     const int sub = ll & 15, p = ll >> 4;
;     f32x4 f[5][2];
; #pragma unroll
;     for (int i = 0; i < 8; ++i) f[i >> 1][i & 1] = h4f(R.raw[i]);
;     { const f32x4 mu = *(const f32x4*)(P.in[I_MU] + h * 64 + 4 * sub), pm = b4f(R.rr[0]), p0 = b4f(R.rr[1]), p1 = b4f(R.rr[2]); f[4][0] = p0 + (pm - p0) * mu; f[4][1] = p1 + (p0 - p1) * mu; }
; #pragma unroll
;     for (int st = 0; st < 2; ++st) { f[0][st][0] = __expf(-f[0][st][0]); f[0][st][1] = __expf(-f[0][st][1]); f[0][st][2] = __expf(-f[0][st][2]); f[0][st][3] = __expf(-f[0][st][3]); }
;     LAS unsigned char* r0 = buf + (2 * p) * RECB + sub * 16; LAS unsigned char* r1 = r0 + RECB;
; #pragma unroll
;     for (int a = 0; a < 5; ++a) { *(LAS f32x4*)(r0 + a * 256) = f[a][0]; *(LAS f32x4*)(r1 + a * 256) = f[a][1]; }
;     *(LAS f32x4*)(r0 + 1344) = f[0][0] * f[2][1];
;     float be = (f[3][0][0] * f[2][1][0] + f[3][0][1] * f[2][1][1]) + (f[3][0][2] * f[2][1][2] + f[3][0][3] * f[2][1][3]);
;     float ka = (f[1][0][0] * f[2][1][0] + f[1][0][1] * f[2][1][1]) + (f[1][0][2] * f[2][1][2] + f[1][0][3] * f[2][1][3]);
;     be = row16_allsum(be); ka = row16_allsum(ka);
;     if (sub == 0) { typedef float f32x2v __attribute__((ext_vector_type(2))); *(LAS f32x2v*)(buf + (2 * p) * RECB + 1600) = (f32x2v){be, ka}; }
;     if (ll < 128) { const int t = ll >> 2, q = ll & 3; *(LAS f32x4*)(buf + t * RECB + 1280 + q * 16) = h4f(R.rv); }
; }
.LBB0_844:
	s_or_b64 exec, exec, s[8:9]
	v_mov_b32_e32 v1, s30
	v_cndmask_b32_e64 v1, v1, v139, s[18:19]
	v_add_u32_e32 v8, v1, v119
	v_ashrrev_i32_e32 v9, 31, v8
	s_lshl_b32 s0, s37, 6
	v_lshlrev_b64 v[8:9], 10, v[8:9]
	v_lshl_add_u64 v[8:9], s[82:83], 0, v[8:9]
	s_lshl_b32 s8, s0, 1
	s_mov_b32 s9, s1
	v_lshl_add_u64 v[8:9], v[8:9], 0, s[8:9]
	s_lshl_b32 s12, s31, 5
	s_mov_b32 s13, s1
	v_lshl_add_u64 v[8:9], v[8:9], 0, s[12:13]
	v_mov_b32_e32 v63, v0
	s_lshl_b32 s12, s0, 2
	v_lshl_add_u64 v[8:9], v[8:9], 0, v[62:63]
	s_waitcnt vmcnt(0)
	v_mov_b32_e32 v218, v30
	v_mov_b32_e32 v219, v31
	v_mov_b32_e32 v220, v32
	v_mov_b32_e32 v221, v33
	v_mov_b32_e32 v222, v2
	v_mov_b32_e32 v223, v3
	v_mov_b32_e32 v224, v20
	v_mov_b32_e32 v225, v21
	v_cvt_f32_f16_e32 v44, v4
	v_cvt_f32_f16_sdwa v45, v4 dst_sel:DWORD dst_unused:UNUSED_PAD src0_sel:WORD_1
	v_cvt_f32_f16_e32 v63, v5
	v_cvt_f32_f16_sdwa v65, v5 dst_sel:DWORD dst_unused:UNUSED_PAD src0_sel:WORD_1
	v_cvt_f32_f16_sdwa v11, v2 dst_sel:DWORD dst_unused:UNUSED_PAD src0_sel:WORD_1
	v_cvt_f32_f16_e32 v10, v2
	v_cvt_f32_f16_sdwa v13, v3 dst_sel:DWORD dst_unused:UNUSED_PAD src0_sel:WORD_1
	v_cvt_f32_f16_e32 v12, v3
	v_cvt_f32_f16_sdwa v3, v20 dst_sel:DWORD dst_unused:UNUSED_PAD src0_sel:WORD_1
	v_cvt_f32_f16_e32 v2, v20
	v_cvt_f32_f16_sdwa v5, v21 dst_sel:DWORD dst_unused:UNUSED_PAD src0_sel:WORD_1
	v_cvt_f32_f16_e32 v4, v21
	v_lshl_add_u64 v[20:21], v[50:51], 0, s[12:13]
	global_load_dwordx2 v[36:37], v[8:9], off
	v_cvt_f32_f16_e32 v1, v6
	v_cvt_f32_f16_sdwa v29, v6 dst_sel:DWORD dst_unused:UNUSED_PAD src0_sel:WORD_1
	v_cvt_f32_f16_e32 v42, v7
	v_cvt_f32_f16_sdwa v43, v7 dst_sel:DWORD dst_unused:UNUSED_PAD src0_sel:WORD_1
	v_cvt_f32_f16_sdwa v212, v22 dst_sel:DWORD dst_unused:UNUSED_PAD src0_sel:WORD_1
	v_cvt_f32_f16_e32 v210, v22
	v_cvt_f32_f16_sdwa v216, v23 dst_sel:DWORD dst_unused:UNUSED_PAD src0_sel:WORD_1
	v_cvt_f32_f16_e32 v214, v23
	global_load_dwordx4 v[22:25], v[20:21], off
	v_lshlrev_b32_e32 v90, 16, v16
	v_and_b32_e32 v91, 0xffff0000, v16
	v_lshlrev_b32_e32 v20, 16, v17
	v_and_b32_e32 v21, 0xffff0000, v17
	v_lshlrev_b32_e32 v16, 16, v14
	v_and_b32_e32 v17, 0xffff0000, v14
	v_lshlrev_b32_e32 v14, 16, v15
	v_and_b32_e32 v15, 0xffff0000, v15
	v_lshlrev_b32_e32 v40, 16, v19
	v_and_b32_e32 v41, 0xffff0000, v19
	v_sub_f32_e32 v21, v21, v15
	v_sub_f32_e32 v20, v20, v14
	v_mul_f32_e32 v1, 0xbfb8aa3b, v1
	v_lshlrev_b32_e32 v38, 16, v18
	v_and_b32_e32 v39, 0xffff0000, v18
	v_sub_f32_e32 v19, v91, v17
	v_sub_f32_e32 v18, v90, v16
	s_waitcnt vmcnt(0)
	v_pk_fma_f32 v[20:21], v[20:21], v[24:25], v[14:15]
	v_sub_f32_e32 v15, v15, v41
	v_sub_f32_e32 v14, v14, v40
	v_pk_fma_f32 v[24:25], v[24:25], v[14:15], v[40:41]
	v_exp_f32_e32 v14, v1
	v_mul_f32_e32 v1, 0xbfb8aa3b, v29
	v_pk_fma_f32 v[18:19], v[18:19], v[22:23], v[16:17]
	v_sub_f32_e32 v17, v17, v39
	v_sub_f32_e32 v16, v16, v38
	v_exp_f32_e32 v15, v1
	v_mul_f32_e32 v1, 0xbfb8aa3b, v42
	v_pk_fma_f32 v[22:23], v[22:23], v[16:17], v[38:39]
	v_exp_f32_e32 v16, v1
	v_mul_f32_e32 v1, 0xbfb8aa3b, v43
	v_exp_f32_e32 v17, v1
	v_mul_f32_e32 v1, 0xbfb8aa3b, v44
	v_exp_f32_e32 v38, v1
	v_mul_f32_e32 v1, 0xbfb8aa3b, v45
	v_exp_f32_e32 v39, v1
	v_mul_f32_e32 v1, 0xbfb8aa3b, v63
	v_exp_f32_e32 v40, v1
	v_mul_f32_e32 v1, 0xbfb8aa3b, v65
	v_exp_f32_e32 v41, v1
	v_add_u32_e32 v1, v121, v48
	ds_write_b128 v1, v[14:17]
	ds_write_b128 v1, v[38:41] offset:1616
	ds_write_b128 v1, v[218:221] offset:256
	ds_write_b128 v1, v[222:225] offset:1872
	ds_write_b128 v1, v[18:21] offset:1024
	ds_write_b128 v1, v[22:25] offset:2640
	v_cvt_f32_f16_e32 v7, v30
	v_cvt_f32_f16_sdwa v9, v30 dst_sel:DWORD dst_unused:UNUSED_PAD src0_sel:WORD_1
	v_cvt_f32_f16_e32 v11, v31
	v_cvt_f32_f16_sdwa v13, v31 dst_sel:DWORD dst_unused:UNUSED_PAD src0_sel:WORD_1
	v_cvt_f32_f16_e32 v6, v34
	v_cvt_f32_f16_sdwa v8, v34 dst_sel:DWORD dst_unused:UNUSED_PAD src0_sel:WORD_1
	v_cvt_f32_f16_e32 v10, v35
	v_cvt_f32_f16_sdwa v12, v35 dst_sel:DWORD dst_unused:UNUSED_PAD src0_sel:WORD_1
	v_cvt_f32_f16_e32 v18, v32
	v_cvt_f32_f16_sdwa v20, v32 dst_sel:DWORD dst_unused:UNUSED_PAD src0_sel:WORD_1
	v_cvt_f32_f16_e32 v22, v33
	v_cvt_f32_f16_sdwa v24, v33 dst_sel:DWORD dst_unused:UNUSED_PAD src0_sel:WORD_1
	v_mov_b32_e32 v2, v7
	v_mov_b32_e32 v3, v9
	v_mov_b32_e32 v4, v11
	v_mov_b32_e32 v5, v13
	v_mov_b32_e32 v2, v6
	v_mov_b32_e32 v3, v8
	v_mov_b32_e32 v4, v10
	v_mov_b32_e32 v5, v12
	ds_write_b128 v1, v[2:5] offset:2128
	v_mov_b32_e32 v2, v18
	v_mov_b32_e32 v3, v20
	v_mov_b32_e32 v4, v22
	v_mov_b32_e32 v5, v24
	v_mov_b32_e32 v2, v10
	v_mov_b32_e32 v3, v12
	v_pk_mul_f32 v[4:5], v[16:17], v[2:3]
	v_mov_b32_e32 v2, v6
	v_mov_b32_e32 v3, v8
	v_mov_b32_e32 v21, v8
	v_mov_b32_e32 v25, v12
	v_pk_mul_f32 v[2:3], v[14:15], v[2:3]
	v_mov_b32_e32 v19, v6
	v_mov_b32_e32 v23, v10
	v_mul_f32_e32 v211, v14, v6
	v_mul_f32_e32 v213, v15, v8
	v_mul_f32_e32 v215, v16, v10
	v_mul_f32_e32 v217, v17, v12
	ds_write_b128 v1, v[210:213] offset:512
	ds_write_b128 v1, v[214:217] offset:1344
	v_pk_mul_f32 v[2:3], v[8:9], v[20:21]
	v_pk_mul_f32 v[4:5], v[12:13], v[24:25]
	v_pk_fma_f32 v[2:3], v[6:7], v[18:19], v[2:3]
	v_pk_fma_f32 v[4:5], v[10:11], v[22:23], v[4:5]
	s_nop 0
	v_pk_add_f32 v[2:3], v[2:3], v[4:5]
	v_mov_b32_e32 v4, v0
	v_mov_b32_e32 v5, v0
	s_nop 0
	v_mov_b32_dpp v4, v2 row_ror:8 row_mask:0xf bank_mask:0xf
	v_mov_b32_dpp v5, v3 row_ror:8 row_mask:0xf bank_mask:0xf
	v_pk_add_f32 v[2:3], v[2:3], v[4:5]
	v_mov_b32_e32 v4, v0
	v_mov_b32_e32 v5, v0
	s_nop 0
	v_mov_b32_dpp v4, v2 row_ror:4 row_mask:0xf bank_mask:0xf
	v_mov_b32_dpp v5, v3 row_ror:4 row_mask:0xf bank_mask:0xf
	v_pk_add_f32 v[2:3], v[2:3], v[4:5]
	v_mov_b32_e32 v4, v0
	v_mov_b32_e32 v5, v0
	s_nop 0
	v_mov_b32_dpp v4, v2 row_ror:2 row_mask:0xf bank_mask:0xf
	v_mov_b32_dpp v5, v3 row_ror:2 row_mask:0xf bank_mask:0xf
	v_pk_add_f32 v[2:3], v[2:3], v[4:5]
	v_mov_b32_e32 v4, v0
	v_mov_b32_e32 v5, v0
	s_nop 0
	v_mov_b32_dpp v4, v2 row_ror:1 row_mask:0xf bank_mask:0xf
	v_mov_b32_dpp v5, v3 row_ror:1 row_mask:0xf bank_mask:0xf
	v_pk_add_f32 v[2:3], v[2:3], v[4:5]
	ds_write_b64 v1, v[2:3] offset:2968
	s_and_saveexec_b64 s[12:13], s[22:23]
	s_cbranch_execz .LBB0_848
	v_cvt_f32_f16_sdwa v3, v36 dst_sel:DWORD dst_unused:UNUSED_PAD src0_sel:WORD_1
	v_cvt_f32_f16_e32 v2, v36
	v_cvt_f32_f16_sdwa v5, v37 dst_sel:DWORD dst_unused:UNUSED_PAD src0_sel:WORD_1
	v_cvt_f32_f16_e32 v4, v37
	ds_write_b32 v250, v2 offset:1344
	ds_write_b32 v250, v3 offset:1360
	ds_write_b32 v250, v4 offset:1376
	ds_write_b32 v250, v5 offset:1392

; #define LAS __attribute__((address_space(3)))
; __device__ __forceinline__ float row16_allsum(float x) { x = ROW_ROR_ADD(x, 8); x = ROW_ROR_ADD(x, 4); x = ROW_ROR_ADD(x, 2); x = ROW_ROR_ADD(x, 1); return x; }
; __device__ __forceinline__ f32x4 h4f(u32x2 r) { const h16x4 hv = __builtin_bit_cast(h16x4, r); return (f32x4){(float)hv[0], (float)hv[1], (float)hv[2], (float)hv[3]}; }
; __device__ __forceinline__ f32x4 b4f(u32x2 r) { return (f32x4){__uint_as_float(r.x << 16), __uint_as_float(r.x & 0xffff0000u), __uint_as_float(r.y << 16), __uint_as_float(r.y & 0xffff0000u)}; }
; __device__ __forceinline__ void scan_cvt_write(const Params& P, int h, const ScanRegs& R, LAS unsigned char* buf, int ll) {
;     const int sub = ll & 15, p = ll >> 4;
;     f32x4 f[5][2];
; #pragma unroll
;     for (int i = 0; i < 8; ++i) f[i >> 1][i & 1] = h4f(R.raw[i]);
;     { const f32x4 mu = *(const f32x4*)(P.in[I_MU] + h * 64 + 4 * sub), pm = b4f(R.rr[0]), p0 = b4f(R.rr[1]), p1 = b4f(R.rr[2]); f[4][0] = p0 + (pm - p0) * mu; f[4][1] = p1 + (p0 - p1) * mu; }
; #pragma unroll
;     for (int st = 0; st < 2; ++st) { f[0][st][0] = __expf(-f[0][st][0]); f[0][st][1] = __expf(-f[0][st][1]); f[0][st][2] = __expf(-f[0][st][2]); f[0][st][3] = __expf(-f[0][st][3]); }
;     LAS unsigned char* r0 = buf + (2 * p) * RECB + sub * 16; LAS unsigned char* r1 = r0 + RECB;
; #pragma unroll
;     for (int a = 0; a < 5; ++a) { *(LAS f32x4*)(r0 + a * 256) = f[a][0]; *(LAS f32x4*)(r1 + a * 256) = f[a][1]; }
;     *(LAS f32x4*)(r0 + 1344) = f[0][0] * f[2][1];
;     float be = (f[3][0][0] * f[2][1][0] + f[3][0][1] * f[2][1][1]) + (f[3][0][2] * f[2][1][2] + f[3][0][3] * f[2][1][3]);
;     float ka = (f[1][0][0] * f[2][1][0] + f[1][0][1] * f[2][1][1]) + (f[1][0][2] * f[2][1][2] + f[1][0][3] * f[2][1][3]);
;     be = row16_allsum(be); ka = row16_allsum(ka);
;     if (sub == 0) { typedef float f32x2v __attribute__((ext_vector_type(2))); *(LAS f32x2v*)(buf + (2 * p) * RECB + 1600) = (f32x2v){be, ka}; }
;     if (ll < 128) { const int t = ll >> 2, q = ll & 3; *(LAS f32x4*)(buf + t * RECB + 1280 + q * 16) = h4f(R.rv); }
; }
.LBB0_860:
	s_cmp_lg_u32 s31, 64
	s_cselect_b64 s[8:9], -1, 0
	s_andn2_b64 vcc, exec, s[72:73]
	s_mov_b64 s[12:13], -1
	s_cbranch_vccnz .LBB0_879
	s_andn2_b64 vcc, exec, s[8:9]
	s_waitcnt lgkmcnt(9)
	v_mov_b64_e32 v[6:7], v[66:67]
	v_mov_b64_e32 v[8:9], v[68:69]
	s_waitcnt lgkmcnt(4)
	v_mov_b64_e32 v[10:11], v[70:71]
	v_mov_b64_e32 v[12:13], v[72:73]
	v_mov_b64_e32 v[14:15], v[74:75]
	v_mov_b64_e32 v[16:17], v[76:77]
	v_mov_b64_e32 v[18:19], v[78:79]
	v_mov_b64_e32 v[20:21], v[80:81]
	v_mov_b64_e32 v[22:23], v[82:83]
	v_mov_b64_e32 v[24:25], v[84:85]
	v_mov_b64_e32 v[26:27], v[86:87]
	v_mov_b64_e32 v[28:29], v[88:89]
	s_cbranch_vccnz .LBB0_873
	global_load_dwordx4 v[6:9], v[90:91], off
	v_cvt_f32_f16_e32 v22, v66
	v_cvt_f32_f16_sdwa v23, v66 dst_sel:DWORD dst_unused:UNUSED_PAD src0_sel:WORD_1
	v_cvt_f32_f16_e32 v24, v67
	v_cvt_f32_f16_sdwa v25, v67 dst_sel:DWORD dst_unused:UNUSED_PAD src0_sel:WORD_1
	s_andn2_b32 s12, 1, s31
	v_cvt_f32_f16_e32 v26, v68
	v_cvt_f32_f16_sdwa v27, v68 dst_sel:DWORD dst_unused:UNUSED_PAD src0_sel:WORD_1
	v_cvt_f32_f16_e32 v28, v69
	v_cvt_f32_f16_sdwa v29, v69 dst_sel:DWORD dst_unused:UNUSED_PAD src0_sel:WORD_1
	v_cvt_f32_f16_sdwa v11, v72 dst_sel:DWORD dst_unused:UNUSED_PAD src0_sel:WORD_1
	v_cvt_f32_f16_e32 v10, v72
	v_cvt_f32_f16_sdwa v13, v73 dst_sel:DWORD dst_unused:UNUSED_PAD src0_sel:WORD_1
	v_cvt_f32_f16_e32 v12, v73
	s_mul_i32 s12, s12, 0xca00
	v_cvt_f32_f16_sdwa v15, v74 dst_sel:DWORD dst_unused:UNUSED_PAD src0_sel:WORD_1
	v_cvt_f32_f16_e32 v14, v74
	v_cvt_f32_f16_sdwa v17, v75 dst_sel:DWORD dst_unused:UNUSED_PAD src0_sel:WORD_1
	v_cvt_f32_f16_e32 v16, v75
	v_lshlrev_b32_e32 v1, 16, v82
	v_lshlrev_b32_e32 v30, 16, v84
	s_add_i32 s36, s12, 0
	v_cvt_f32_f16_sdwa v19, v80 dst_sel:DWORD dst_unused:UNUSED_PAD src0_sel:WORD_1
	v_cvt_f32_f16_e32 v18, v80
	v_cvt_f32_f16_sdwa v21, v81 dst_sel:DWORD dst_unused:UNUSED_PAD src0_sel:WORD_1
	v_cvt_f32_f16_e32 v20, v81
	v_and_b32_e32 v63, 0xffff0000, v82
	v_lshlrev_b32_e32 v65, 16, v83
	s_waitcnt lgkmcnt(2)
	v_and_b32_e32 v106, 0xffff0000, v83
	v_and_b32_e32 v31, 0xffff0000, v84
	v_lshlrev_b32_e32 v32, 16, v85
	v_and_b32_e32 v33, 0xffff0000, v85
	v_sub_f32_e32 v140, v1, v30
	v_add_u32_e32 v1, s36, v120
	v_mul_f32_e32 v22, 0xbfb8aa3b, v22
	v_mul_f32_e32 v23, 0xbfb8aa3b, v23
	v_mul_f32_e32 v24, 0xbfb8aa3b, v24
	v_mul_f32_e32 v25, 0xbfb8aa3b, v25
	v_lshlrev_b32_e32 v34, 16, v86
	v_and_b32_e32 v35, 0xffff0000, v86
	v_lshlrev_b32_e32 v36, 16, v87
	v_and_b32_e32 v37, 0xffff0000, v87
	v_cvt_f32_f16_e32 v39, v70
	v_cvt_f32_f16_sdwa v41, v70 dst_sel:DWORD dst_unused:UNUSED_PAD src0_sel:WORD_1
	v_cvt_f32_f16_e32 v43, v71
	v_cvt_f32_f16_sdwa v45, v71 dst_sel:DWORD dst_unused:UNUSED_PAD src0_sel:WORD_1
	v_sub_f32_e32 v141, v63, v31
	v_sub_f32_e32 v143, v106, v33
	v_sub_f32_e32 v142, v65, v32
	v_mul_f32_e32 v26, 0xbfb8aa3b, v26
	v_mul_f32_e32 v27, 0xbfb8aa3b, v27
	v_mul_f32_e32 v28, 0xbfb8aa3b, v28
	v_mul_f32_e32 v29, 0xbfb8aa3b, v29
	v_add_u32_e32 v63, v1, v48
	v_exp_f32_e32 v22, v22
	v_exp_f32_e32 v23, v23
	v_exp_f32_e32 v24, v24
	v_exp_f32_e32 v25, v25
	v_cvt_f32_f16_e32 v38, v76
	v_cvt_f32_f16_sdwa v40, v76 dst_sel:DWORD dst_unused:UNUSED_PAD src0_sel:WORD_1
	v_cvt_f32_f16_e32 v42, v77
	v_cvt_f32_f16_sdwa v44, v77 dst_sel:DWORD dst_unused:UNUSED_PAD src0_sel:WORD_1
	v_sub_f32_e32 v145, v31, v35
	v_sub_f32_e32 v144, v30, v34
	v_sub_f32_e32 v147, v33, v37
	v_sub_f32_e32 v146, v32, v36
	v_exp_f32_e32 v26, v26
	v_exp_f32_e32 v27, v27
	v_exp_f32_e32 v28, v28
	v_exp_f32_e32 v29, v29
	ds_write_b128 v63, v[22:25]
	ds_write_b128 v63, v[26:29] offset:1616
	s_waitcnt lgkmcnt(6)
	v_cvt_f32_f16_e32 v110, v78
	v_cvt_f32_f16_sdwa v14, v79 dst_sel:DWORD dst_unused:UNUSED_PAD src0_sel:WORD_1
	v_mov_b32_e32 v15, v44
	v_mov_b32_e32 v111, v38
	s_waitcnt vmcnt(0)
	v_pk_fma_f32 v[12:13], v[142:143], v[8:9], v[32:33]
	v_pk_fma_f32 v[10:11], v[140:141], v[6:7], v[30:31]
	v_pk_fma_f32 v[8:9], v[146:147], v[8:9], v[36:37]
	v_pk_fma_f32 v[6:7], v[144:145], v[6:7], v[34:35]
	ds_write_b128 v63, v[10:13] offset:1024
	ds_write_b128 v63, v[6:9] offset:2640
	v_cvt_f32_f16_sdwa v10, v78 dst_sel:DWORD dst_unused:UNUSED_PAD src0_sel:WORD_1
	v_cvt_f32_f16_e32 v12, v79
	v_mov_b32_e32 v6, v39
	v_mov_b32_e32 v7, v41
	v_mov_b32_e32 v8, v43
	v_mov_b32_e32 v9, v45
	v_mov_b32_e32 v218, v70
	v_mov_b32_e32 v219, v71
	v_mov_b32_e32 v220, v78
	v_mov_b32_e32 v221, v79
	v_mov_b32_e32 v222, v72
	v_mov_b32_e32 v223, v73
	v_mov_b32_e32 v224, v80
	v_mov_b32_e32 v225, v81
	ds_write_b128 v63, v[218:221] offset:256
	ds_write_b128 v63, v[222:225] offset:1872
	v_mov_b32_e32 v6, v38
	v_mov_b32_e32 v7, v40
	v_mov_b32_e32 v8, v42
	v_mov_b32_e32 v9, v44
	ds_write_b128 v63, v[6:9] offset:2128
	v_mov_b32_e32 v6, v110
	v_mov_b32_e32 v7, v10
	v_mov_b32_e32 v8, v12
	v_mov_b32_e32 v9, v14
	v_mov_b32_e32 v6, v42
	v_mov_b32_e32 v7, v44
	v_pk_mul_f32 v[8:9], v[24:25], v[6:7]
	v_mov_b32_e32 v6, v38
	v_mov_b32_e32 v7, v40
	v_mov_b32_e32 v11, v40
	v_pk_mul_f32 v[6:7], v[22:23], v[6:7]
	v_mov_b32_e32 v13, v42
	v_cvt_f32_f16_e32 v210, v74
	v_mul_f32_e32 v211, v22, v38
	v_cvt_f32_f16_sdwa v212, v74 dst_sel:DWORD dst_unused:UNUSED_PAD src0_sel:WORD_1
	v_mul_f32_e32 v213, v23, v40
	v_cvt_f32_f16_e32 v214, v75
	v_mul_f32_e32 v215, v24, v42
	v_cvt_f32_f16_sdwa v216, v75 dst_sel:DWORD dst_unused:UNUSED_PAD src0_sel:WORD_1
	v_mul_f32_e32 v217, v25, v44
	ds_write_b128 v63, v[210:213] offset:512
	ds_write_b128 v63, v[214:217] offset:1344
	v_pk_mul_f32 v[6:7], v[40:41], v[10:11]
	v_pk_mul_f32 v[8:9], v[44:45], v[14:15]
	v_pk_fma_f32 v[6:7], v[38:39], v[110:111], v[6:7]
	v_pk_fma_f32 v[8:9], v[42:43], v[12:13], v[8:9]
	s_nop 0
	v_pk_add_f32 v[6:7], v[6:7], v[8:9]
	v_mov_b32_e32 v8, v0
	v_mov_b32_e32 v9, v0
	s_nop 0
	v_mov_b32_dpp v8, v6 row_ror:8 row_mask:0xf bank_mask:0xf
	v_mov_b32_dpp v9, v7 row_ror:8 row_mask:0xf bank_mask:0xf
	v_pk_add_f32 v[6:7], v[6:7], v[8:9]
	v_mov_b32_e32 v8, v0
	v_mov_b32_e32 v9, v0
	s_nop 0
	v_mov_b32_dpp v8, v6 row_ror:4 row_mask:0xf bank_mask:0xf
	v_mov_b32_dpp v9, v7 row_ror:4 row_mask:0xf bank_mask:0xf
	v_pk_add_f32 v[6:7], v[6:7], v[8:9]
	v_mov_b32_e32 v8, v0
	v_mov_b32_e32 v9, v0
	s_nop 0
	v_mov_b32_dpp v8, v6 row_ror:2 row_mask:0xf bank_mask:0xf
	v_mov_b32_dpp v9, v7 row_ror:2 row_mask:0xf bank_mask:0xf
	v_pk_add_f32 v[6:7], v[6:7], v[8:9]
	v_mov_b32_e32 v8, v0
	v_mov_b32_e32 v9, v0
	s_nop 0
	v_mov_b32_dpp v8, v6 row_ror:1 row_mask:0xf bank_mask:0xf
	v_mov_b32_dpp v9, v7 row_ror:1 row_mask:0xf bank_mask:0xf
	v_pk_add_f32 v[6:7], v[6:7], v[8:9]
	ds_write_b64 v63, v[6:7] offset:2968
	s_and_saveexec_b64 s[12:13], s[22:23]
	s_cbranch_execz .LBB0_866
	v_cvt_f32_f16_sdwa v7, v88 dst_sel:DWORD dst_unused:UNUSED_PAD src0_sel:WORD_1
	v_cvt_f32_f16_e32 v6, v88
	v_cvt_f32_f16_sdwa v9, v89 dst_sel:DWORD dst_unused:UNUSED_PAD src0_sel:WORD_1
	v_cvt_f32_f16_e32 v8, v89
	v_add_u32_e32 v1, s36, v250
	ds_write_b32 v1, v6 offset:1344
	ds_write_b32 v1, v7 offset:1360
	ds_write_b32 v1, v8 offset:1376
	ds_write_b32 v1, v9 offset:1392

; __device__ __forceinline__ float row16_allsum(float x) { x = ROW_ROR_ADD(x, 8); x = ROW_ROR_ADD(x, 4); x = ROW_ROR_ADD(x, 2); x = ROW_ROR_ADD(x, 1); return x; }
; __device__ __forceinline__ float dot4(f32x4 a, f32x4 b) { return __builtin_fmaf(a[3], b[3], __builtin_fmaf(a[2], b[2], __builtin_fmaf(a[1], b[1], a[0] * b[0]))); }
; __device__ __forceinline__ void scan_phase(const Params& P, LAS unsigned char* lds, int tid, int wid, int lane) {
;     ...
;                 SC_LOADP(0, 0);
;                 for (int t0 = 0; t0 < nsteps; t0 += 16) {
;                     float ykeep = 0.f;
; #pragma unroll
;                     for (int u = 0; u < 8; ++u) {
;                         SC_LOADP((u + 1) & 1, t0 + 2 * u + 2);
;                         const int s = u & 1;
;                         float dA = dot4(S, kk0[s]), dB = dot4(S, wk0[s]);
;                         dA = row16_allsum(dA); dB = row16_allsum(dB);
;                         const float sa0 = -dA;
;                         const f32x4 S0 = S * w0[s] + (b0[s] * sa0 + kh0[s] * v0[s]);
;                         const float sa1 = -(dB + sa0 * bk[s].x + v0[s] * bk[s].y);
;                         const f32x4 S1 = S0 * w1[s] + (b1[s] * sa1 + kh1[s] * v1[s]);
;                         float y0 = dot4(S0, r0[s]), y1 = dot4(S1, r1[s]);
;                         y0 = row16_allsum(y0); y1 = row16_allsum(y1);
;                         ykeep = (jq == 2 * u) ? y0 : ykeep; ykeep = (jq == 2 * u + 1) ? y1 : ykeep;
;                         S = S1;
;                     }
.LBB0_879:
	s_andn2_b64 vcc, exec, s[12:13]
	s_cbranch_vccnz .LBB0_858
	s_and_b32 s12, s31, 1
	s_mul_i32 s13, s12, 0xca00
	s_add_i32 s36, s13, 0
	v_add_u32_e32 v1, s36, v48
	s_waitcnt vmcnt(3) lgkmcnt(13)
	ds_read_b128 v[14:17], v1
	s_waitcnt vmcnt(1) lgkmcnt(13)
	ds_read_b128 v[22:25], v1 offset:256
	s_waitcnt lgkmcnt(13)
	ds_read_b128 v[42:45], v1 offset:512
	s_waitcnt lgkmcnt(13)
	s_waitcnt lgkmcnt(13)
	ds_read_b128 v[6:9], v1 offset:1024
	s_waitcnt lgkmcnt(13)
	ds_read_b128 v[38:41], v1 offset:1344
	s_waitcnt lgkmcnt(13)
	ds_read_b128 v[18:21], v1 offset:1616
	s_waitcnt vmcnt(0) lgkmcnt(13)
	ds_read_b128 v[26:29], v1 offset:1872
	s_waitcnt lgkmcnt(13)
	s_waitcnt lgkmcnt(13)
	ds_read_b128 v[10:13], v1 offset:2640
	v_lshl_add_u32 v63, v134, 2, s36
	v_mov_b32_e32 v65, s36
	s_waitcnt lgkmcnt(13)
	ds_read_b128 v[108:111], v63 offset:2960
	v_lshl_add_u32 v65, s12, 11, v135
	s_mov_b32 s37, 0
	s_mov_b64 s[12:13], -1
.LBB0_881:
	s_mul_i32 vcc_lo, s37, 0x650
	v_add_u32_e32 v140, vcc_lo, v1
	v_add_u32_e32 v141, vcc_lo, v63
	ds_read_b128 v[152:155], v140 offset:3744
	ds_read_b128 v[164:167], v140 offset:4576
	ds_read_b128 v[148:151], v140 offset:3488
	ds_read_b128 v[184:187], v141 offset:6192
	ds_read_b128 v[172:175], v140 offset:5104
	ds_read_b128 v[144:147], v140 offset:3232
	ds_read_b128 v[168:171], v140 offset:4848
	ds_read_b128 v[160:163], v140 offset:4256
	ds_read_b128 v[180:183], v140 offset:5872
	s_waitcnt lgkmcnt(9)
	v_pk_mul_f32 v[42:43], v[2:3], v[42:43] op_sel_hi:[0,1]
	v_pk_fma_f32 v[42:43], v[2:3], v[44:45], v[42:43] op_sel:[1,0,0] op_sel_hi:[1,1,1]
	v_pk_fma_f32 v[42:43], v[4:5], v[38:39], v[42:43] op_sel:[0,0,0] op_sel_hi:[0,1,1]
	v_pk_fma_f32 v[42:43], v[4:5], v[40:41], v[42:43] op_sel:[1,0,0] op_sel_hi:[1,1,1]
	v_fma_mix_f32 v190, v22, v108, 0 op_sel:[0,0,0] op_sel_hi:[1,0,0]
	v_fma_mix_f32 v191, v22, v108, 0 op_sel:[1,0,0] op_sel_hi:[1,0,0]
	v_add_f32_dpp v42, v42, v42 row_ror:8 row_mask:0xf bank_mask:0xf bound_ctrl:1
	v_add_f32_dpp v43, v43, v43 row_ror:8 row_mask:0xf bank_mask:0xf bound_ctrl:1
	v_fma_mix_f32 v192, v23, v108, 0 op_sel:[0,0,0] op_sel_hi:[1,0,0]
	v_add_f32_dpp v42, v42, v42 row_ror:4 row_mask:0xf bank_mask:0xf bound_ctrl:1
	v_add_f32_dpp v43, v43, v43 row_ror:4 row_mask:0xf bank_mask:0xf bound_ctrl:1
	v_fma_mix_f32 v193, v23, v108, 0 op_sel:[1,0,0] op_sel_hi:[1,0,0]
	v_add_f32_dpp v42, v42, v42 row_ror:2 row_mask:0xf bank_mask:0xf bound_ctrl:1
	v_add_f32_dpp v43, v43, v43 row_ror:2 row_mask:0xf bank_mask:0xf bound_ctrl:1
	v_fma_mix_f32 v44, v26, v109, 0 op_sel:[0,0,0] op_sel_hi:[1,0,0]
	v_add_f32_dpp v42, v42, v42 row_ror:1 row_mask:0xf bank_mask:0xf bound_ctrl:1
	v_add_f32_dpp v43, v43, v43 row_ror:1 row_mask:0xf bank_mask:0xf bound_ctrl:1
	v_fma_mix_f32 v45, v26, v109, 0 op_sel:[1,0,0] op_sel_hi:[1,0,0]
	v_fma_mix_f32 v40, v27, v109, 0 op_sel:[0,0,0] op_sel_hi:[1,0,0]
	v_fma_mix_f32 v190, v24, -v42, v190 op_sel:[0,0,0] op_sel_hi:[1,0,0]
	v_fma_mix_f32 v191, v24, -v42, v191 op_sel:[1,0,0] op_sel_hi:[1,0,0]
	v_fma_mix_f32 v192, v25, -v42, v192 op_sel:[0,0,0] op_sel_hi:[1,0,0]
	v_fma_mix_f32 v193, v25, -v42, v193 op_sel:[1,0,0] op_sel_hi:[1,0,0]
	v_fma_f32 v43, -v42, v110, v43
	v_pk_fma_f32 v[190:191], v[2:3], v[14:15], v[190:191]
	v_fma_mix_f32 v41, v27, v109, 0 op_sel:[1,0,0] op_sel_hi:[1,0,0]
	v_pk_fma_f32 v[192:193], v[4:5], v[16:17], v[192:193]
	v_fma_f32 v43, v108, v111, v43
	v_pk_mul_f32 v[6:7], v[190:191], v[6:7]
	v_fma_mix_f32 v44, v28, -v43, v44 op_sel:[0,0,0] op_sel_hi:[1,0,0]
	v_fma_mix_f32 v45, v28, -v43, v45 op_sel:[1,0,0] op_sel_hi:[1,0,0]
	v_pk_fma_f32 v[6:7], v[192:193], v[8:9], v[6:7]
	v_fma_mix_f32 v40, v29, -v43, v40 op_sel:[0,0,0] op_sel_hi:[1,0,0]
	v_fma_mix_f32 v41, v29, -v43, v41 op_sel:[1,0,0] op_sel_hi:[1,0,0]
	v_add_f32_e32 v194, v6, v7
	v_pk_fma_f32 v[2:3], v[190:191], v[18:19], v[44:45]
	v_pk_fma_f32 v[4:5], v[192:193], v[20:21], v[40:41]
	v_pk_mul_f32 v[10:11], v[2:3], v[10:11]
	v_pk_fma_f32 v[10:11], v[4:5], v[12:13], v[10:11]
	v_add_f32_e32 v195, v10, v11
	ds_read_b128 v[42:45], v140 offset:6976
	ds_read_b128 v[38:41], v140 offset:7808
	ds_read_b128 v[22:25], v140 offset:6720
	ds_read_b128 v[108:111], v141 offset:9424
	ds_read_b128 v[26:29], v140 offset:8336
	ds_read_b128 v[14:17], v140 offset:6464
	ds_read_b128 v[18:21], v140 offset:8080
	ds_read_b128 v[6:9], v140 offset:7488
	ds_read_b128 v[10:13], v140 offset:9104
	s_waitcnt lgkmcnt(9)
; __device__ __forceinline__ float row16_allsum(float x) { x = ROW_ROR_ADD(x, 8); x = ROW_ROR_ADD(x, 4); x = ROW_ROR_ADD(x, 2); x = ROW_ROR_ADD(x, 1); return x; }
; __device__ __forceinline__ float dot4(f32x4 a, f32x4 b) { return __builtin_fmaf(a[3], b[3], __builtin_fmaf(a[2], b[2], __builtin_fmaf(a[1], b[1], a[0] * b[0]))); }
; __device__ __forceinline__ void scan_phase(const Params& P, LAS unsigned char* lds, int tid, int wid, int lane) {
;     ...
;                 SC_LOADP(0, 0);
;                 for (int t0 = 0; t0 < nsteps; t0 += 16) {
;                     float ykeep = 0.f;
; #pragma unroll
;                     for (int u = 0; u < 8; ++u) {
;                         SC_LOADP((u + 1) & 1, t0 + 2 * u + 2);
;                         const int s = u & 1;
;                         float dA = dot4(S, kk0[s]), dB = dot4(S, wk0[s]);
;                         dA = row16_allsum(dA); dB = row16_allsum(dB);
;                         const float sa0 = -dA;
;                         const f32x4 S0 = S * w0[s] + (b0[s] * sa0 + kh0[s] * v0[s]);
;                         const float sa1 = -(dB + sa0 * bk[s].x + v0[s] * bk[s].y);
;                         const f32x4 S1 = S0 * w1[s] + (b1[s] * sa1 + kh1[s] * v1[s]);
;                         float y0 = dot4(S0, r0[s]), y1 = dot4(S1, r1[s]);
;                         y0 = row16_allsum(y0); y1 = row16_allsum(y1);
;                         ykeep = (jq == 2 * u) ? y0 : ykeep; ykeep = (jq == 2 * u + 1) ? y1 : ykeep;
;                         S = S1;
;                     }
	v_pk_mul_f32 v[152:153], v[2:3], v[152:153] op_sel_hi:[0,1]
	v_pk_fma_f32 v[152:153], v[2:3], v[154:155], v[152:153] op_sel:[1,0,0] op_sel_hi:[1,1,1]
	v_pk_fma_f32 v[152:153], v[4:5], v[164:165], v[152:153] op_sel:[0,0,0] op_sel_hi:[0,1,1]
	v_pk_fma_f32 v[152:153], v[4:5], v[166:167], v[152:153] op_sel:[1,0,0] op_sel_hi:[1,1,1]
	v_fma_mix_f32 v190, v148, v184, 0 op_sel:[0,0,0] op_sel_hi:[1,0,0]
	v_fma_mix_f32 v191, v148, v184, 0 op_sel:[1,0,0] op_sel_hi:[1,0,0]
	v_add_f32_dpp v152, v152, v152 row_ror:8 row_mask:0xf bank_mask:0xf bound_ctrl:1
	v_add_f32_dpp v153, v153, v153 row_ror:8 row_mask:0xf bank_mask:0xf bound_ctrl:1
	v_fma_mix_f32 v192, v149, v184, 0 op_sel:[0,0,0] op_sel_hi:[1,0,0]
	v_add_f32_dpp v152, v152, v152 row_ror:4 row_mask:0xf bank_mask:0xf bound_ctrl:1
	v_add_f32_dpp v153, v153, v153 row_ror:4 row_mask:0xf bank_mask:0xf bound_ctrl:1
	v_fma_mix_f32 v193, v149, v184, 0 op_sel:[1,0,0] op_sel_hi:[1,0,0]
	v_add_f32_dpp v152, v152, v152 row_ror:2 row_mask:0xf bank_mask:0xf bound_ctrl:1
	v_add_f32_dpp v153, v153, v153 row_ror:2 row_mask:0xf bank_mask:0xf bound_ctrl:1
	v_fma_mix_f32 v154, v172, v185, 0 op_sel:[0,0,0] op_sel_hi:[1,0,0]
	v_add_f32_dpp v152, v152, v152 row_ror:1 row_mask:0xf bank_mask:0xf bound_ctrl:1
	v_add_f32_dpp v153, v153, v153 row_ror:1 row_mask:0xf bank_mask:0xf bound_ctrl:1
	v_fma_mix_f32 v155, v172, v185, 0 op_sel:[1,0,0] op_sel_hi:[1,0,0]
	v_fma_mix_f32 v166, v173, v185, 0 op_sel:[0,0,0] op_sel_hi:[1,0,0]
	v_fma_mix_f32 v190, v150, -v152, v190 op_sel:[0,0,0] op_sel_hi:[1,0,0]
	v_fma_mix_f32 v191, v150, -v152, v191 op_sel:[1,0,0] op_sel_hi:[1,0,0]
	v_fma_mix_f32 v192, v151, -v152, v192 op_sel:[0,0,0] op_sel_hi:[1,0,0]
	v_fma_mix_f32 v193, v151, -v152, v193 op_sel:[1,0,0] op_sel_hi:[1,0,0]
	v_fma_f32 v153, -v152, v186, v153
	v_pk_fma_f32 v[190:191], v[2:3], v[144:145], v[190:191]
	v_fma_mix_f32 v167, v173, v185, 0 op_sel:[1,0,0] op_sel_hi:[1,0,0]
	v_pk_fma_f32 v[192:193], v[4:5], v[146:147], v[192:193]
	v_fma_f32 v153, v184, v187, v153
	v_pk_mul_f32 v[160:161], v[190:191], v[160:161]
	v_fma_mix_f32 v154, v174, -v153, v154 op_sel:[0,0,0] op_sel_hi:[1,0,0]
	v_fma_mix_f32 v155, v174, -v153, v155 op_sel:[1,0,0] op_sel_hi:[1,0,0]
	v_pk_fma_f32 v[160:161], v[192:193], v[162:163], v[160:161]
	v_fma_mix_f32 v166, v175, -v153, v166 op_sel:[0,0,0] op_sel_hi:[1,0,0]
	v_fma_mix_f32 v167, v175, -v153, v167 op_sel:[1,0,0] op_sel_hi:[1,0,0]
	v_add_f32_e32 v196, v160, v161
	v_pk_fma_f32 v[2:3], v[190:191], v[168:169], v[154:155]
	v_pk_fma_f32 v[4:5], v[192:193], v[170:171], v[166:167]
	v_pk_mul_f32 v[180:181], v[2:3], v[180:181]
	v_pk_fma_f32 v[180:181], v[4:5], v[182:183], v[180:181]
	v_add_f32_e32 v197, v180, v181
	v_add_f32_dpp v194, v194, v194 row_ror:8 row_mask:0xf bank_mask:0xf bound_ctrl:1
	v_add_f32_dpp v195, v195, v195 row_ror:8 row_mask:0xf bank_mask:0xf bound_ctrl:1
	v_add_f32_dpp v196, v196, v196 row_ror:8 row_mask:0xf bank_mask:0xf bound_ctrl:1
	v_add_f32_dpp v197, v197, v197 row_ror:8 row_mask:0xf bank_mask:0xf bound_ctrl:1
	v_cndmask_b32_e64 v194, v194, v195, s[42:43]
	v_cndmask_b32_e64 v196, v196, v197, s[42:43]
	ds_read_b128 v[152:155], v140 offset:10208
	ds_read_b128 v[164:167], v140 offset:11040
	ds_read_b128 v[148:151], v140 offset:9952
	ds_read_b128 v[184:187], v141 offset:12656
	ds_read_b128 v[172:175], v140 offset:11568
	ds_read_b128 v[144:147], v140 offset:9696
	ds_read_b128 v[168:171], v140 offset:11312
	ds_read_b128 v[160:163], v140 offset:10720
	ds_read_b128 v[180:183], v140 offset:12336
	v_add_f32_dpp v194, v194, v194 row_half_mirror row_mask:0xf bank_mask:0xf bound_ctrl:1
	v_add_f32_dpp v196, v196, v196 row_half_mirror row_mask:0xf bank_mask:0xf bound_ctrl:1
	s_waitcnt lgkmcnt(9)
	v_cndmask_b32_e64 v194, v194, v196, s[44:45]
	v_pk_mul_f32 v[42:43], v[2:3], v[42:43] op_sel_hi:[0,1]
	v_pk_fma_f32 v[42:43], v[2:3], v[44:45], v[42:43] op_sel:[1,0,0] op_sel_hi:[1,1,1]
	v_add_f32_dpp v194, v194, v194 quad_perm:[1,0,3,2] row_mask:0xf bank_mask:0xf bound_ctrl:1
	v_pk_fma_f32 v[42:43], v[4:5], v[38:39], v[42:43] op_sel:[0,0,0] op_sel_hi:[0,1,1]
	v_pk_fma_f32 v[42:43], v[4:5], v[40:41], v[42:43] op_sel:[1,0,0] op_sel_hi:[1,1,1]
	v_add_f32_dpp v194, v194, v194 quad_perm:[2,3,0,1] row_mask:0xf bank_mask:0xf bound_ctrl:1
	v_fma_mix_f32 v190, v22, v108, 0 op_sel:[0,0,0] op_sel_hi:[1,0,0]
	v_fma_mix_f32 v191, v22, v108, 0 op_sel:[1,0,0] op_sel_hi:[1,0,0]
	v_cndmask_b32_e64 v143, v143, v194, s[46:47]
	v_add_f32_dpp v42, v42, v42 row_ror:8 row_mask:0xf bank_mask:0xf bound_ctrl:1
	v_add_f32_dpp v43, v43, v43 row_ror:8 row_mask:0xf bank_mask:0xf bound_ctrl:1
	v_fma_mix_f32 v192, v23, v108, 0 op_sel:[0,0,0] op_sel_hi:[1,0,0]
	v_add_f32_dpp v42, v42, v42 row_ror:4 row_mask:0xf bank_mask:0xf bound_ctrl:1
	v_add_f32_dpp v43, v43, v43 row_ror:4 row_mask:0xf bank_mask:0xf bound_ctrl:1
	v_fma_mix_f32 v193, v23, v108, 0 op_sel:[1,0,0] op_sel_hi:[1,0,0]
	v_add_f32_dpp v42, v42, v42 row_ror:2 row_mask:0xf bank_mask:0xf bound_ctrl:1
	v_add_f32_dpp v43, v43, v43 row_ror:2 row_mask:0xf bank_mask:0xf bound_ctrl:1
	v_fma_mix_f32 v44, v26, v109, 0 op_sel:[0,0,0] op_sel_hi:[1,0,0]
	v_add_f32_dpp v42, v42, v42 row_ror:1 row_mask:0xf bank_mask:0xf bound_ctrl:1
	v_add_f32_dpp v43, v43, v43 row_ror:1 row_mask:0xf bank_mask:0xf bound_ctrl:1
	v_fma_mix_f32 v45, v26, v109, 0 op_sel:[1,0,0] op_sel_hi:[1,0,0]
	v_fma_mix_f32 v40, v27, v109, 0 op_sel:[0,0,0] op_sel_hi:[1,0,0]
	v_fma_mix_f32 v190, v24, -v42, v190 op_sel:[0,0,0] op_sel_hi:[1,0,0]
	v_fma_mix_f32 v191, v24, -v42, v191 op_sel:[1,0,0] op_sel_hi:[1,0,0]
	v_fma_mix_f32 v192, v25, -v42, v192 op_sel:[0,0,0] op_sel_hi:[1,0,0]
	v_fma_mix_f32 v193, v25, -v42, v193 op_sel:[1,0,0] op_sel_hi:[1,0,0]
	v_fma_f32 v43, -v42, v110, v43
	v_pk_fma_f32 v[190:191], v[2:3], v[14:15], v[190:191]
	v_fma_mix_f32 v41, v27, v109, 0 op_sel:[1,0,0] op_sel_hi:[1,0,0]
	v_pk_fma_f32 v[192:193], v[4:5], v[16:17], v[192:193]
	v_fma_f32 v43, v108, v111, v43
	v_pk_mul_f32 v[6:7], v[190:191], v[6:7]
	v_fma_mix_f32 v44, v28, -v43, v44 op_sel:[0,0,0] op_sel_hi:[1,0,0]
	v_fma_mix_f32 v45, v28, -v43, v45 op_sel:[1,0,0] op_sel_hi:[1,0,0]
	v_pk_fma_f32 v[6:7], v[192:193], v[8:9], v[6:7]
	v_fma_mix_f32 v40, v29, -v43, v40 op_sel:[0,0,0] op_sel_hi:[1,0,0]
	v_fma_mix_f32 v41, v29, -v43, v41 op_sel:[1,0,0] op_sel_hi:[1,0,0]
	v_add_f32_e32 v194, v6, v7
	v_pk_fma_f32 v[2:3], v[190:191], v[18:19], v[44:45]
	v_pk_fma_f32 v[4:5], v[192:193], v[20:21], v[40:41]
	v_pk_mul_f32 v[10:11], v[2:3], v[10:11]
	v_pk_fma_f32 v[10:11], v[4:5], v[12:13], v[10:11]
	v_add_f32_e32 v195, v10, v11
	ds_read_b128 v[42:45], v140 offset:13440
	ds_read_b128 v[38:41], v140 offset:14272
	ds_read_b128 v[22:25], v140 offset:13184
	ds_read_b128 v[108:111], v141 offset:15888
	ds_read_b128 v[26:29], v140 offset:14800
	ds_read_b128 v[14:17], v140 offset:12928
	ds_read_b128 v[18:21], v140 offset:14544
	ds_read_b128 v[6:9], v140 offset:13952
	ds_read_b128 v[10:13], v140 offset:15568
	s_waitcnt lgkmcnt(9)
; __device__ __forceinline__ float row16_allsum(float x) { x = ROW_ROR_ADD(x, 8); x = ROW_ROR_ADD(x, 4); x = ROW_ROR_ADD(x, 2); x = ROW_ROR_ADD(x, 1); return x; }
; __device__ __forceinline__ float dot4(f32x4 a, f32x4 b) { return __builtin_fmaf(a[3], b[3], __builtin_fmaf(a[2], b[2], __builtin_fmaf(a[1], b[1], a[0] * b[0]))); }
; __device__ __forceinline__ void scan_phase(const Params& P, LAS unsigned char* lds, int tid, int wid, int lane) {
;     ...
;                 SC_LOADP(0, 0);
;                 for (int t0 = 0; t0 < nsteps; t0 += 16) {
;                     float ykeep = 0.f;
; #pragma unroll
;                     for (int u = 0; u < 8; ++u) {
;                         SC_LOADP((u + 1) & 1, t0 + 2 * u + 2);
;                         const int s = u & 1;
;                         float dA = dot4(S, kk0[s]), dB = dot4(S, wk0[s]);
;                         dA = row16_allsum(dA); dB = row16_allsum(dB);
;                         const float sa0 = -dA;
;                         const f32x4 S0 = S * w0[s] + (b0[s] * sa0 + kh0[s] * v0[s]);
;                         const float sa1 = -(dB + sa0 * bk[s].x + v0[s] * bk[s].y);
;                         const f32x4 S1 = S0 * w1[s] + (b1[s] * sa1 + kh1[s] * v1[s]);
;                         float y0 = dot4(S0, r0[s]), y1 = dot4(S1, r1[s]);
;                         y0 = row16_allsum(y0); y1 = row16_allsum(y1);
;                         ykeep = (jq == 2 * u) ? y0 : ykeep; ykeep = (jq == 2 * u + 1) ? y1 : ykeep;
;                         S = S1;
;                     }
	v_pk_mul_f32 v[152:153], v[2:3], v[152:153] op_sel_hi:[0,1]
	v_pk_fma_f32 v[152:153], v[2:3], v[154:155], v[152:153] op_sel:[1,0,0] op_sel_hi:[1,1,1]
	v_pk_fma_f32 v[152:153], v[4:5], v[164:165], v[152:153] op_sel:[0,0,0] op_sel_hi:[0,1,1]
	v_pk_fma_f32 v[152:153], v[4:5], v[166:167], v[152:153] op_sel:[1,0,0] op_sel_hi:[1,1,1]
	v_fma_mix_f32 v190, v148, v184, 0 op_sel:[0,0,0] op_sel_hi:[1,0,0]
	v_fma_mix_f32 v191, v148, v184, 0 op_sel:[1,0,0] op_sel_hi:[1,0,0]
	v_add_f32_dpp v152, v152, v152 row_ror:8 row_mask:0xf bank_mask:0xf bound_ctrl:1
	v_add_f32_dpp v153, v153, v153 row_ror:8 row_mask:0xf bank_mask:0xf bound_ctrl:1
	v_fma_mix_f32 v192, v149, v184, 0 op_sel:[0,0,0] op_sel_hi:[1,0,0]
	v_add_f32_dpp v152, v152, v152 row_ror:4 row_mask:0xf bank_mask:0xf bound_ctrl:1
	v_add_f32_dpp v153, v153, v153 row_ror:4 row_mask:0xf bank_mask:0xf bound_ctrl:1
	v_fma_mix_f32 v193, v149, v184, 0 op_sel:[1,0,0] op_sel_hi:[1,0,0]
	v_add_f32_dpp v152, v152, v152 row_ror:2 row_mask:0xf bank_mask:0xf bound_ctrl:1
	v_add_f32_dpp v153, v153, v153 row_ror:2 row_mask:0xf bank_mask:0xf bound_ctrl:1
	v_fma_mix_f32 v154, v172, v185, 0 op_sel:[0,0,0] op_sel_hi:[1,0,0]
	v_add_f32_dpp v152, v152, v152 row_ror:1 row_mask:0xf bank_mask:0xf bound_ctrl:1
	v_add_f32_dpp v153, v153, v153 row_ror:1 row_mask:0xf bank_mask:0xf bound_ctrl:1
	v_fma_mix_f32 v155, v172, v185, 0 op_sel:[1,0,0] op_sel_hi:[1,0,0]
	v_fma_mix_f32 v166, v173, v185, 0 op_sel:[0,0,0] op_sel_hi:[1,0,0]
	v_fma_mix_f32 v190, v150, -v152, v190 op_sel:[0,0,0] op_sel_hi:[1,0,0]
	v_fma_mix_f32 v191, v150, -v152, v191 op_sel:[1,0,0] op_sel_hi:[1,0,0]
	v_fma_mix_f32 v192, v151, -v152, v192 op_sel:[0,0,0] op_sel_hi:[1,0,0]
	v_fma_mix_f32 v193, v151, -v152, v193 op_sel:[1,0,0] op_sel_hi:[1,0,0]
	v_fma_f32 v153, -v152, v186, v153
	v_pk_fma_f32 v[190:191], v[2:3], v[144:145], v[190:191]
	v_fma_mix_f32 v167, v173, v185, 0 op_sel:[1,0,0] op_sel_hi:[1,0,0]
	v_pk_fma_f32 v[192:193], v[4:5], v[146:147], v[192:193]
	v_fma_f32 v153, v184, v187, v153
	v_pk_mul_f32 v[160:161], v[190:191], v[160:161]
	v_fma_mix_f32 v154, v174, -v153, v154 op_sel:[0,0,0] op_sel_hi:[1,0,0]
	v_fma_mix_f32 v155, v174, -v153, v155 op_sel:[1,0,0] op_sel_hi:[1,0,0]
	v_pk_fma_f32 v[160:161], v[192:193], v[162:163], v[160:161]
	v_fma_mix_f32 v166, v175, -v153, v166 op_sel:[0,0,0] op_sel_hi:[1,0,0]
	v_fma_mix_f32 v167, v175, -v153, v167 op_sel:[1,0,0] op_sel_hi:[1,0,0]
	v_add_f32_e32 v196, v160, v161
	v_pk_fma_f32 v[2:3], v[190:191], v[168:169], v[154:155]
	v_pk_fma_f32 v[4:5], v[192:193], v[170:171], v[166:167]
	v_pk_mul_f32 v[180:181], v[2:3], v[180:181]
	v_pk_fma_f32 v[180:181], v[4:5], v[182:183], v[180:181]
	v_add_f32_e32 v197, v180, v181
	v_add_f32_dpp v194, v194, v194 row_ror:8 row_mask:0xf bank_mask:0xf bound_ctrl:1
	v_add_f32_dpp v195, v195, v195 row_ror:8 row_mask:0xf bank_mask:0xf bound_ctrl:1
	v_add_f32_dpp v196, v196, v196 row_ror:8 row_mask:0xf bank_mask:0xf bound_ctrl:1
	v_add_f32_dpp v197, v197, v197 row_ror:8 row_mask:0xf bank_mask:0xf bound_ctrl:1
	v_cndmask_b32_e64 v194, v194, v195, s[42:43]
	v_cndmask_b32_e64 v196, v196, v197, s[42:43]
	ds_read_b128 v[152:155], v140 offset:16672
	ds_read_b128 v[164:167], v140 offset:17504
	ds_read_b128 v[148:151], v140 offset:16416
	ds_read_b128 v[184:187], v141 offset:19120
	ds_read_b128 v[172:175], v140 offset:18032
	ds_read_b128 v[144:147], v140 offset:16160
	ds_read_b128 v[168:171], v140 offset:17776
	ds_read_b128 v[160:163], v140 offset:17184
	ds_read_b128 v[180:183], v140 offset:18800
	v_add_f32_dpp v194, v194, v194 row_half_mirror row_mask:0xf bank_mask:0xf bound_ctrl:1
	v_add_f32_dpp v196, v196, v196 row_half_mirror row_mask:0xf bank_mask:0xf bound_ctrl:1
	s_waitcnt lgkmcnt(9)
	v_cndmask_b32_e64 v194, v194, v196, s[44:45]
	v_pk_mul_f32 v[42:43], v[2:3], v[42:43] op_sel_hi:[0,1]
	v_pk_fma_f32 v[42:43], v[2:3], v[44:45], v[42:43] op_sel:[1,0,0] op_sel_hi:[1,1,1]
	v_add_f32_dpp v194, v194, v194 quad_perm:[1,0,3,2] row_mask:0xf bank_mask:0xf bound_ctrl:1
	v_pk_fma_f32 v[42:43], v[4:5], v[38:39], v[42:43] op_sel:[0,0,0] op_sel_hi:[0,1,1]
	v_pk_fma_f32 v[42:43], v[4:5], v[40:41], v[42:43] op_sel:[1,0,0] op_sel_hi:[1,1,1]
	v_add_f32_dpp v194, v194, v194 quad_perm:[2,3,0,1] row_mask:0xf bank_mask:0xf bound_ctrl:1
	v_fma_mix_f32 v190, v22, v108, 0 op_sel:[0,0,0] op_sel_hi:[1,0,0]
	v_fma_mix_f32 v191, v22, v108, 0 op_sel:[1,0,0] op_sel_hi:[1,0,0]
	v_cndmask_b32_e64 v143, v143, v194, s[48:49]
	v_add_f32_dpp v42, v42, v42 row_ror:8 row_mask:0xf bank_mask:0xf bound_ctrl:1
	v_add_f32_dpp v43, v43, v43 row_ror:8 row_mask:0xf bank_mask:0xf bound_ctrl:1
	v_fma_mix_f32 v192, v23, v108, 0 op_sel:[0,0,0] op_sel_hi:[1,0,0]
	v_add_f32_dpp v42, v42, v42 row_ror:4 row_mask:0xf bank_mask:0xf bound_ctrl:1
	v_add_f32_dpp v43, v43, v43 row_ror:4 row_mask:0xf bank_mask:0xf bound_ctrl:1
	v_fma_mix_f32 v193, v23, v108, 0 op_sel:[1,0,0] op_sel_hi:[1,0,0]
	v_add_f32_dpp v42, v42, v42 row_ror:2 row_mask:0xf bank_mask:0xf bound_ctrl:1
	v_add_f32_dpp v43, v43, v43 row_ror:2 row_mask:0xf bank_mask:0xf bound_ctrl:1
	v_fma_mix_f32 v44, v26, v109, 0 op_sel:[0,0,0] op_sel_hi:[1,0,0]
	v_add_f32_dpp v42, v42, v42 row_ror:1 row_mask:0xf bank_mask:0xf bound_ctrl:1
	v_add_f32_dpp v43, v43, v43 row_ror:1 row_mask:0xf bank_mask:0xf bound_ctrl:1
	v_fma_mix_f32 v45, v26, v109, 0 op_sel:[1,0,0] op_sel_hi:[1,0,0]
	v_fma_mix_f32 v40, v27, v109, 0 op_sel:[0,0,0] op_sel_hi:[1,0,0]
	v_fma_mix_f32 v190, v24, -v42, v190 op_sel:[0,0,0] op_sel_hi:[1,0,0]
	v_fma_mix_f32 v191, v24, -v42, v191 op_sel:[1,0,0] op_sel_hi:[1,0,0]
	v_fma_mix_f32 v192, v25, -v42, v192 op_sel:[0,0,0] op_sel_hi:[1,0,0]
	v_fma_mix_f32 v193, v25, -v42, v193 op_sel:[1,0,0] op_sel_hi:[1,0,0]
	v_fma_f32 v43, -v42, v110, v43
	v_pk_fma_f32 v[190:191], v[2:3], v[14:15], v[190:191]
	v_fma_mix_f32 v41, v27, v109, 0 op_sel:[1,0,0] op_sel_hi:[1,0,0]
	v_pk_fma_f32 v[192:193], v[4:5], v[16:17], v[192:193]
	v_fma_f32 v43, v108, v111, v43
	v_pk_mul_f32 v[6:7], v[190:191], v[6:7]
	v_fma_mix_f32 v44, v28, -v43, v44 op_sel:[0,0,0] op_sel_hi:[1,0,0]
	v_fma_mix_f32 v45, v28, -v43, v45 op_sel:[1,0,0] op_sel_hi:[1,0,0]
	v_pk_fma_f32 v[6:7], v[192:193], v[8:9], v[6:7]
	v_fma_mix_f32 v40, v29, -v43, v40 op_sel:[0,0,0] op_sel_hi:[1,0,0]
	v_fma_mix_f32 v41, v29, -v43, v41 op_sel:[1,0,0] op_sel_hi:[1,0,0]
	v_add_f32_e32 v194, v6, v7
	v_pk_fma_f32 v[2:3], v[190:191], v[18:19], v[44:45]
	v_pk_fma_f32 v[4:5], v[192:193], v[20:21], v[40:41]
	v_pk_mul_f32 v[10:11], v[2:3], v[10:11]
	v_pk_fma_f32 v[10:11], v[4:5], v[12:13], v[10:11]
	v_add_f32_e32 v195, v10, v11
	ds_read_b128 v[42:45], v140 offset:19904
	ds_read_b128 v[38:41], v140 offset:20736
	ds_read_b128 v[22:25], v140 offset:19648
	ds_read_b128 v[108:111], v141 offset:22352
	ds_read_b128 v[26:29], v140 offset:21264
	ds_read_b128 v[14:17], v140 offset:19392
	ds_read_b128 v[18:21], v140 offset:21008
	ds_read_b128 v[6:9], v140 offset:20416
	ds_read_b128 v[10:13], v140 offset:22032
	s_waitcnt lgkmcnt(9)
; __device__ __forceinline__ float row16_allsum(float x) { x = ROW_ROR_ADD(x, 8); x = ROW_ROR_ADD(x, 4); x = ROW_ROR_ADD(x, 2); x = ROW_ROR_ADD(x, 1); return x; }
; __device__ __forceinline__ float dot4(f32x4 a, f32x4 b) { return __builtin_fmaf(a[3], b[3], __builtin_fmaf(a[2], b[2], __builtin_fmaf(a[1], b[1], a[0] * b[0]))); }
; __device__ __forceinline__ void scan_phase(const Params& P, LAS unsigned char* lds, int tid, int wid, int lane) {
;     ...
;                 SC_LOADP(0, 0);
;                 for (int t0 = 0; t0 < nsteps; t0 += 16) {
;                     float ykeep = 0.f;
; #pragma unroll
;                     for (int u = 0; u < 8; ++u) {
;                         SC_LOADP((u + 1) & 1, t0 + 2 * u + 2);
;                         const int s = u & 1;
;                         float dA = dot4(S, kk0[s]), dB = dot4(S, wk0[s]);
;                         dA = row16_allsum(dA); dB = row16_allsum(dB);
;                         const float sa0 = -dA;
;                         const f32x4 S0 = S * w0[s] + (b0[s] * sa0 + kh0[s] * v0[s]);
;                         const float sa1 = -(dB + sa0 * bk[s].x + v0[s] * bk[s].y);
;                         const f32x4 S1 = S0 * w1[s] + (b1[s] * sa1 + kh1[s] * v1[s]);
;                         float y0 = dot4(S0, r0[s]), y1 = dot4(S1, r1[s]);
;                         y0 = row16_allsum(y0); y1 = row16_allsum(y1);
;                         ykeep = (jq == 2 * u) ? y0 : ykeep; ykeep = (jq == 2 * u + 1) ? y1 : ykeep;
;                         S = S1;
;                     }
	v_pk_mul_f32 v[152:153], v[2:3], v[152:153] op_sel_hi:[0,1]
	v_pk_fma_f32 v[152:153], v[2:3], v[154:155], v[152:153] op_sel:[1,0,0] op_sel_hi:[1,1,1]
	v_pk_fma_f32 v[152:153], v[4:5], v[164:165], v[152:153] op_sel:[0,0,0] op_sel_hi:[0,1,1]
	v_pk_fma_f32 v[152:153], v[4:5], v[166:167], v[152:153] op_sel:[1,0,0] op_sel_hi:[1,1,1]
	v_fma_mix_f32 v190, v148, v184, 0 op_sel:[0,0,0] op_sel_hi:[1,0,0]
	v_fma_mix_f32 v191, v148, v184, 0 op_sel:[1,0,0] op_sel_hi:[1,0,0]
	v_add_f32_dpp v152, v152, v152 row_ror:8 row_mask:0xf bank_mask:0xf bound_ctrl:1
	v_add_f32_dpp v153, v153, v153 row_ror:8 row_mask:0xf bank_mask:0xf bound_ctrl:1
	v_fma_mix_f32 v192, v149, v184, 0 op_sel:[0,0,0] op_sel_hi:[1,0,0]
	v_add_f32_dpp v152, v152, v152 row_ror:4 row_mask:0xf bank_mask:0xf bound_ctrl:1
	v_add_f32_dpp v153, v153, v153 row_ror:4 row_mask:0xf bank_mask:0xf bound_ctrl:1
	v_fma_mix_f32 v193, v149, v184, 0 op_sel:[1,0,0] op_sel_hi:[1,0,0]
	v_add_f32_dpp v152, v152, v152 row_ror:2 row_mask:0xf bank_mask:0xf bound_ctrl:1
	v_add_f32_dpp v153, v153, v153 row_ror:2 row_mask:0xf bank_mask:0xf bound_ctrl:1
	v_fma_mix_f32 v154, v172, v185, 0 op_sel:[0,0,0] op_sel_hi:[1,0,0]
	v_add_f32_dpp v152, v152, v152 row_ror:1 row_mask:0xf bank_mask:0xf bound_ctrl:1
	v_add_f32_dpp v153, v153, v153 row_ror:1 row_mask:0xf bank_mask:0xf bound_ctrl:1
	v_fma_mix_f32 v155, v172, v185, 0 op_sel:[1,0,0] op_sel_hi:[1,0,0]
	v_fma_mix_f32 v166, v173, v185, 0 op_sel:[0,0,0] op_sel_hi:[1,0,0]
	v_fma_mix_f32 v190, v150, -v152, v190 op_sel:[0,0,0] op_sel_hi:[1,0,0]
	v_fma_mix_f32 v191, v150, -v152, v191 op_sel:[1,0,0] op_sel_hi:[1,0,0]
	v_fma_mix_f32 v192, v151, -v152, v192 op_sel:[0,0,0] op_sel_hi:[1,0,0]
	v_fma_mix_f32 v193, v151, -v152, v193 op_sel:[1,0,0] op_sel_hi:[1,0,0]
	v_fma_f32 v153, -v152, v186, v153
	v_pk_fma_f32 v[190:191], v[2:3], v[144:145], v[190:191]
	v_fma_mix_f32 v167, v173, v185, 0 op_sel:[1,0,0] op_sel_hi:[1,0,0]
	v_pk_fma_f32 v[192:193], v[4:5], v[146:147], v[192:193]
	v_fma_f32 v153, v184, v187, v153
	v_pk_mul_f32 v[160:161], v[190:191], v[160:161]
	v_fma_mix_f32 v154, v174, -v153, v154 op_sel:[0,0,0] op_sel_hi:[1,0,0]
	v_fma_mix_f32 v155, v174, -v153, v155 op_sel:[1,0,0] op_sel_hi:[1,0,0]
	v_pk_fma_f32 v[160:161], v[192:193], v[162:163], v[160:161]
	v_fma_mix_f32 v166, v175, -v153, v166 op_sel:[0,0,0] op_sel_hi:[1,0,0]
	v_fma_mix_f32 v167, v175, -v153, v167 op_sel:[1,0,0] op_sel_hi:[1,0,0]
	v_add_f32_e32 v196, v160, v161
	v_pk_fma_f32 v[2:3], v[190:191], v[168:169], v[154:155]
	v_pk_fma_f32 v[4:5], v[192:193], v[170:171], v[166:167]
	v_pk_mul_f32 v[180:181], v[2:3], v[180:181]
	v_pk_fma_f32 v[180:181], v[4:5], v[182:183], v[180:181]
	v_add_f32_e32 v197, v180, v181
	v_add_f32_dpp v194, v194, v194 row_ror:8 row_mask:0xf bank_mask:0xf bound_ctrl:1
	v_add_f32_dpp v195, v195, v195 row_ror:8 row_mask:0xf bank_mask:0xf bound_ctrl:1
	v_add_f32_dpp v196, v196, v196 row_ror:8 row_mask:0xf bank_mask:0xf bound_ctrl:1
	v_add_f32_dpp v197, v197, v197 row_ror:8 row_mask:0xf bank_mask:0xf bound_ctrl:1
	v_cndmask_b32_e64 v194, v194, v195, s[42:43]
	v_cndmask_b32_e64 v196, v196, v197, s[42:43]
	ds_read_b128 v[152:155], v140 offset:23136
	ds_read_b128 v[164:167], v140 offset:23968
	ds_read_b128 v[148:151], v140 offset:22880
	ds_read_b128 v[184:187], v141 offset:25584
	ds_read_b128 v[172:175], v140 offset:24496
	ds_read_b128 v[144:147], v140 offset:22624
	ds_read_b128 v[168:171], v140 offset:24240
	ds_read_b128 v[160:163], v140 offset:23648
	ds_read_b128 v[180:183], v140 offset:25264
	v_add_f32_dpp v194, v194, v194 row_half_mirror row_mask:0xf bank_mask:0xf bound_ctrl:1
	v_add_f32_dpp v196, v196, v196 row_half_mirror row_mask:0xf bank_mask:0xf bound_ctrl:1
	s_waitcnt lgkmcnt(9)
	v_cndmask_b32_e64 v194, v194, v196, s[44:45]
	v_pk_mul_f32 v[42:43], v[2:3], v[42:43] op_sel_hi:[0,1]
	v_pk_fma_f32 v[42:43], v[2:3], v[44:45], v[42:43] op_sel:[1,0,0] op_sel_hi:[1,1,1]
	v_add_f32_dpp v194, v194, v194 quad_perm:[1,0,3,2] row_mask:0xf bank_mask:0xf bound_ctrl:1
	v_pk_fma_f32 v[42:43], v[4:5], v[38:39], v[42:43] op_sel:[0,0,0] op_sel_hi:[0,1,1]
	v_pk_fma_f32 v[42:43], v[4:5], v[40:41], v[42:43] op_sel:[1,0,0] op_sel_hi:[1,1,1]
	v_add_f32_dpp v194, v194, v194 quad_perm:[2,3,0,1] row_mask:0xf bank_mask:0xf bound_ctrl:1
	v_fma_mix_f32 v190, v22, v108, 0 op_sel:[0,0,0] op_sel_hi:[1,0,0]
	v_fma_mix_f32 v191, v22, v108, 0 op_sel:[1,0,0] op_sel_hi:[1,0,0]
	v_cndmask_b32_e64 v143, v143, v194, s[50:51]
	v_add_f32_dpp v42, v42, v42 row_ror:8 row_mask:0xf bank_mask:0xf bound_ctrl:1
	v_add_f32_dpp v43, v43, v43 row_ror:8 row_mask:0xf bank_mask:0xf bound_ctrl:1
	v_fma_mix_f32 v192, v23, v108, 0 op_sel:[0,0,0] op_sel_hi:[1,0,0]
	v_add_f32_dpp v42, v42, v42 row_ror:4 row_mask:0xf bank_mask:0xf bound_ctrl:1
	v_add_f32_dpp v43, v43, v43 row_ror:4 row_mask:0xf bank_mask:0xf bound_ctrl:1
	v_fma_mix_f32 v193, v23, v108, 0 op_sel:[1,0,0] op_sel_hi:[1,0,0]
	v_add_f32_dpp v42, v42, v42 row_ror:2 row_mask:0xf bank_mask:0xf bound_ctrl:1
	v_add_f32_dpp v43, v43, v43 row_ror:2 row_mask:0xf bank_mask:0xf bound_ctrl:1
	v_fma_mix_f32 v44, v26, v109, 0 op_sel:[0,0,0] op_sel_hi:[1,0,0]
	v_add_f32_dpp v42, v42, v42 row_ror:1 row_mask:0xf bank_mask:0xf bound_ctrl:1
	v_add_f32_dpp v43, v43, v43 row_ror:1 row_mask:0xf bank_mask:0xf bound_ctrl:1
	v_fma_mix_f32 v45, v26, v109, 0 op_sel:[1,0,0] op_sel_hi:[1,0,0]
	v_fma_mix_f32 v40, v27, v109, 0 op_sel:[0,0,0] op_sel_hi:[1,0,0]
	v_fma_mix_f32 v190, v24, -v42, v190 op_sel:[0,0,0] op_sel_hi:[1,0,0]
	v_fma_mix_f32 v191, v24, -v42, v191 op_sel:[1,0,0] op_sel_hi:[1,0,0]
	v_fma_mix_f32 v192, v25, -v42, v192 op_sel:[0,0,0] op_sel_hi:[1,0,0]
	v_fma_mix_f32 v193, v25, -v42, v193 op_sel:[1,0,0] op_sel_hi:[1,0,0]
	v_fma_f32 v43, -v42, v110, v43
	v_pk_fma_f32 v[190:191], v[2:3], v[14:15], v[190:191]
	v_fma_mix_f32 v41, v27, v109, 0 op_sel:[1,0,0] op_sel_hi:[1,0,0]
	v_pk_fma_f32 v[192:193], v[4:5], v[16:17], v[192:193]
	v_fma_f32 v43, v108, v111, v43
	v_pk_mul_f32 v[6:7], v[190:191], v[6:7]
	v_fma_mix_f32 v44, v28, -v43, v44 op_sel:[0,0,0] op_sel_hi:[1,0,0]
	v_fma_mix_f32 v45, v28, -v43, v45 op_sel:[1,0,0] op_sel_hi:[1,0,0]
	v_pk_fma_f32 v[6:7], v[192:193], v[8:9], v[6:7]
	v_fma_mix_f32 v40, v29, -v43, v40 op_sel:[0,0,0] op_sel_hi:[1,0,0]
	v_fma_mix_f32 v41, v29, -v43, v41 op_sel:[1,0,0] op_sel_hi:[1,0,0]
	v_add_f32_e32 v194, v6, v7
	v_pk_fma_f32 v[2:3], v[190:191], v[18:19], v[44:45]
	v_pk_fma_f32 v[4:5], v[192:193], v[20:21], v[40:41]
	v_pk_mul_f32 v[10:11], v[2:3], v[10:11]
	v_pk_fma_f32 v[10:11], v[4:5], v[12:13], v[10:11]
	v_add_f32_e32 v195, v10, v11
	ds_read_b128 v[42:45], v140 offset:26368
	ds_read_b128 v[38:41], v140 offset:27200
	ds_read_b128 v[22:25], v140 offset:26112
	ds_read_b128 v[108:111], v141 offset:28816
	ds_read_b128 v[26:29], v140 offset:27728
	ds_read_b128 v[14:17], v140 offset:25856
	ds_read_b128 v[18:21], v140 offset:27472
	ds_read_b128 v[6:9], v140 offset:26880
	ds_read_b128 v[10:13], v140 offset:28496
	s_waitcnt lgkmcnt(9)
; __device__ __forceinline__ float row16_allsum(float x) { x = ROW_ROR_ADD(x, 8); x = ROW_ROR_ADD(x, 4); x = ROW_ROR_ADD(x, 2); x = ROW_ROR_ADD(x, 1); return x; }
; __device__ __forceinline__ float dot4(f32x4 a, f32x4 b) { return __builtin_fmaf(a[3], b[3], __builtin_fmaf(a[2], b[2], __builtin_fmaf(a[1], b[1], a[0] * b[0]))); }
; __device__ __forceinline__ void scan_phase(const Params& P, LAS unsigned char* lds, int tid, int wid, int lane) {
;     ...
;                 SC_LOADP(0, 0);
;                 for (int t0 = 0; t0 < nsteps; t0 += 16) {
;                     float ykeep = 0.f;
; #pragma unroll
;                     for (int u = 0; u < 8; ++u) {
;                         SC_LOADP((u + 1) & 1, t0 + 2 * u + 2);
;                         const int s = u & 1;
;                         float dA = dot4(S, kk0[s]), dB = dot4(S, wk0[s]);
;                         dA = row16_allsum(dA); dB = row16_allsum(dB);
;                         const float sa0 = -dA;
;                         const f32x4 S0 = S * w0[s] + (b0[s] * sa0 + kh0[s] * v0[s]);
;                         const float sa1 = -(dB + sa0 * bk[s].x + v0[s] * bk[s].y);
;                         const f32x4 S1 = S0 * w1[s] + (b1[s] * sa1 + kh1[s] * v1[s]);
;                         float y0 = dot4(S0, r0[s]), y1 = dot4(S1, r1[s]);
;                         y0 = row16_allsum(y0); y1 = row16_allsum(y1);
;                         ykeep = (jq == 2 * u) ? y0 : ykeep; ykeep = (jq == 2 * u + 1) ? y1 : ykeep;
;                         S = S1;
;                     }
;                     yb[(t0 + jq) * 16 + il] = ykeep;
	v_pk_mul_f32 v[152:153], v[2:3], v[152:153] op_sel_hi:[0,1]
	v_pk_fma_f32 v[152:153], v[2:3], v[154:155], v[152:153] op_sel:[1,0,0] op_sel_hi:[1,1,1]
	v_pk_fma_f32 v[152:153], v[4:5], v[164:165], v[152:153] op_sel:[0,0,0] op_sel_hi:[0,1,1]
	v_pk_fma_f32 v[152:153], v[4:5], v[166:167], v[152:153] op_sel:[1,0,0] op_sel_hi:[1,1,1]
	v_fma_mix_f32 v190, v148, v184, 0 op_sel:[0,0,0] op_sel_hi:[1,0,0]
	v_fma_mix_f32 v191, v148, v184, 0 op_sel:[1,0,0] op_sel_hi:[1,0,0]
	v_add_f32_dpp v152, v152, v152 row_ror:8 row_mask:0xf bank_mask:0xf bound_ctrl:1
	v_add_f32_dpp v153, v153, v153 row_ror:8 row_mask:0xf bank_mask:0xf bound_ctrl:1
	v_fma_mix_f32 v192, v149, v184, 0 op_sel:[0,0,0] op_sel_hi:[1,0,0]
	v_add_f32_dpp v152, v152, v152 row_ror:4 row_mask:0xf bank_mask:0xf bound_ctrl:1
	v_add_f32_dpp v153, v153, v153 row_ror:4 row_mask:0xf bank_mask:0xf bound_ctrl:1
	v_fma_mix_f32 v193, v149, v184, 0 op_sel:[1,0,0] op_sel_hi:[1,0,0]
	v_add_f32_dpp v152, v152, v152 row_ror:2 row_mask:0xf bank_mask:0xf bound_ctrl:1
	v_add_f32_dpp v153, v153, v153 row_ror:2 row_mask:0xf bank_mask:0xf bound_ctrl:1
	v_fma_mix_f32 v154, v172, v185, 0 op_sel:[0,0,0] op_sel_hi:[1,0,0]
	v_add_f32_dpp v152, v152, v152 row_ror:1 row_mask:0xf bank_mask:0xf bound_ctrl:1
	v_add_f32_dpp v153, v153, v153 row_ror:1 row_mask:0xf bank_mask:0xf bound_ctrl:1
	v_fma_mix_f32 v155, v172, v185, 0 op_sel:[1,0,0] op_sel_hi:[1,0,0]
	v_fma_mix_f32 v166, v173, v185, 0 op_sel:[0,0,0] op_sel_hi:[1,0,0]
	v_fma_mix_f32 v190, v150, -v152, v190 op_sel:[0,0,0] op_sel_hi:[1,0,0]
	v_fma_mix_f32 v191, v150, -v152, v191 op_sel:[1,0,0] op_sel_hi:[1,0,0]
	v_fma_mix_f32 v192, v151, -v152, v192 op_sel:[0,0,0] op_sel_hi:[1,0,0]
	v_fma_mix_f32 v193, v151, -v152, v193 op_sel:[1,0,0] op_sel_hi:[1,0,0]
	v_fma_f32 v153, -v152, v186, v153
	v_pk_fma_f32 v[190:191], v[2:3], v[144:145], v[190:191]
	v_fma_mix_f32 v167, v173, v185, 0 op_sel:[1,0,0] op_sel_hi:[1,0,0]
	v_pk_fma_f32 v[192:193], v[4:5], v[146:147], v[192:193]
	v_fma_f32 v153, v184, v187, v153
	v_pk_mul_f32 v[160:161], v[190:191], v[160:161]
	v_fma_mix_f32 v154, v174, -v153, v154 op_sel:[0,0,0] op_sel_hi:[1,0,0]
	v_fma_mix_f32 v155, v174, -v153, v155 op_sel:[1,0,0] op_sel_hi:[1,0,0]
	v_pk_fma_f32 v[160:161], v[192:193], v[162:163], v[160:161]
	v_fma_mix_f32 v166, v175, -v153, v166 op_sel:[0,0,0] op_sel_hi:[1,0,0]
	v_fma_mix_f32 v167, v175, -v153, v167 op_sel:[1,0,0] op_sel_hi:[1,0,0]
	v_add_f32_e32 v196, v160, v161
	v_pk_fma_f32 v[2:3], v[190:191], v[168:169], v[154:155]
	v_pk_fma_f32 v[4:5], v[192:193], v[170:171], v[166:167]
	v_pk_mul_f32 v[180:181], v[2:3], v[180:181]
	v_pk_fma_f32 v[180:181], v[4:5], v[182:183], v[180:181]
	v_add_f32_e32 v197, v180, v181
	v_add_f32_dpp v194, v194, v194 row_ror:8 row_mask:0xf bank_mask:0xf bound_ctrl:1
	v_add_f32_dpp v195, v195, v195 row_ror:8 row_mask:0xf bank_mask:0xf bound_ctrl:1
	v_add_f32_dpp v196, v196, v196 row_ror:8 row_mask:0xf bank_mask:0xf bound_ctrl:1
	v_add_f32_dpp v197, v197, v197 row_ror:8 row_mask:0xf bank_mask:0xf bound_ctrl:1
	v_cndmask_b32_e64 v194, v194, v195, s[42:43]
	v_cndmask_b32_e64 v196, v196, v197, s[42:43]
	s_and_b64 vcc, s[8:9], s[12:13]
	s_mov_b64 s[12:13], 0
	v_add_f32_dpp v194, v194, v194 row_half_mirror row_mask:0xf bank_mask:0xf bound_ctrl:1
	v_add_f32_dpp v196, v196, v196 row_half_mirror row_mask:0xf bank_mask:0xf bound_ctrl:1
	v_lshl_add_u32 v193, s37, 6, v255
	v_cndmask_b32_e64 v194, v194, v196, s[44:45]
	s_andn2_b64 vcc, exec, vcc
	v_add_u32_e32 v193, v193, v65
	v_add_f32_dpp v194, v194, v194 quad_perm:[1,0,3,2] row_mask:0xf bank_mask:0xf bound_ctrl:1
	s_mov_b32 s37, 16
	s_nop 0
	v_add_f32_dpp v194, v194, v194 quad_perm:[2,3,0,1] row_mask:0xf bank_mask:0xf bound_ctrl:1
	v_cndmask_b32_e64 v143, v143, v194, s[52:53]
	ds_write_b32 v193, v143
	s_cbranch_vccz .LBB0_881
	s_branch .LBB0_859
